# adaLN modulation loop software-pipelined: next 8-row group loaded while the current one is consumed (16 loads in flight per wave)
# speedup vs baseline: 1.0172x; 1.0002x over previous
; __device__ __forceinline__ float fsig(float x) { return __builtin_amdgcn_rcpf(1.0f + __expf(-x)); }
; #define LAS __attribute__((address_space(3)))
; #define LDS_WAIT() asm volatile("s_waitcnt lgkmcnt(0)" ::: "memory")
; __device__ __forceinline__ void phase_convert(const Args& a, LAS unsigned char* lds) {
;     ...
;     for (int it = blockIdx.x; it < DEPTH * 96; it += gridDim.x) {
;         const int l = it / 96, ch = it % 96, j = ch * 64 + lane, i0 = wave * 256;
;         LAS float* red = (LAS float*)(lds + 131072);
; #pragma unroll
;         for (int b = 0; b < 4; ++b)
; #pragma unroll
;             for (int q = 0; q < 4; ++q) { const int ii = q * 64 + lane; const float cv = a.in[I_C][b * D + i0 + ii]; scr[b * 256 + ii] = cv * fsig(cv); }
;         LDS_WAIT(); asm volatile("" ::: "memory");
;         float a0 = 0.f, a1 = 0.f, a2 = 0.f, a3 = 0.f;
;         const float* wp = a.in[I_ADAW] + ((size_t)l * D + i0) * (3 * D) + j;
.LBB0_461:
	global_load_dword v30, v[2:3], off
	global_load_dword v31, v[4:5], off offset:256
	global_load_dword v32, v[4:5], off offset:512
	global_load_dword v33, v[4:5], off offset:768
	global_load_dword v34, v[6:7], off
	global_load_dword v35, v[8:9], off
	global_load_dword v36, v[10:11], off
	global_load_dword v37, v[12:13], off
	global_load_dword v42, v[14:15], off
	global_load_dword v43, v[16:17], off
	global_load_dword v44, v[18:19], off
	global_load_dword v45, v[20:21], off
	global_load_dword v46, v[22:23], off
	global_load_dword v47, v[24:25], off
	global_load_dword v48, v[26:27], off
	global_load_dword v49, v[28:29], off
	s_mul_hi_i32 s38, s45, 0x2aaaaaab
	s_lshr_b32 s39, s38, 31
	s_ashr_i32 s38, s38, 4
	s_add_i32 s38, s38, s39
	s_mul_i32 s39, s38, 0x60
	s_sub_i32 s39, s45, s39
	s_waitcnt vmcnt(15)
	v_mul_f32_e32 v50, 0xbfb8aa3b, v30
	s_waitcnt vmcnt(14)
	v_mul_f32_e32 v51, 0xbfb8aa3b, v31
	s_waitcnt vmcnt(13)
	v_mul_f32_e32 v52, 0xbfb8aa3b, v32
	s_waitcnt vmcnt(12)
	v_mul_f32_e32 v53, 0xbfb8aa3b, v33
	s_waitcnt vmcnt(11)
	v_mul_f32_e32 v54, 0xbfb8aa3b, v34
	s_waitcnt vmcnt(10)
	v_mul_f32_e32 v55, 0xbfb8aa3b, v35
	s_waitcnt vmcnt(9)
	v_mul_f32_e32 v56, 0xbfb8aa3b, v36
	s_waitcnt vmcnt(8)
	v_mul_f32_e32 v57, 0xbfb8aa3b, v37
	s_waitcnt vmcnt(7)
	v_mul_f32_e32 v58, 0xbfb8aa3b, v42
	s_waitcnt vmcnt(6)
	v_mul_f32_e32 v59, 0xbfb8aa3b, v43
	v_exp_f32_e32 v50, v50
	v_exp_f32_e32 v51, v51
	v_exp_f32_e32 v52, v52
	v_exp_f32_e32 v53, v53
	v_exp_f32_e32 v54, v54
	v_exp_f32_e32 v55, v55
	v_exp_f32_e32 v56, v56
	v_exp_f32_e32 v57, v57
	v_exp_f32_e32 v58, v58
	v_exp_f32_e32 v59, v59
	v_add_f32_e32 v50, 1.0, v50
	v_add_f32_e32 v51, 1.0, v51
	v_add_f32_e32 v52, 1.0, v52
	v_add_f32_e32 v53, 1.0, v53
	v_add_f32_e32 v54, 1.0, v54
	v_add_f32_e32 v55, 1.0, v55
	v_add_f32_e32 v56, 1.0, v56
	v_add_f32_e32 v57, 1.0, v57
	v_add_f32_e32 v58, 1.0, v58
	v_add_f32_e32 v59, 1.0, v59
	v_rcp_f32_e32 v50, v50
	v_rcp_f32_e32 v51, v51
	v_rcp_f32_e32 v52, v52
	v_rcp_f32_e32 v53, v53
	v_rcp_f32_e32 v54, v54
	v_rcp_f32_e32 v55, v55
	v_rcp_f32_e32 v56, v56
	v_rcp_f32_e32 v57, v57
	v_rcp_f32_e32 v58, v58
	v_rcp_f32_e32 v59, v59
	s_waitcnt vmcnt(5)
	v_mul_f32_e32 v60, 0xbfb8aa3b, v44
	s_waitcnt vmcnt(4)
	v_mul_f32_e32 v61, 0xbfb8aa3b, v45
	s_waitcnt vmcnt(3)
	v_mul_f32_e32 v62, 0xbfb8aa3b, v46
	s_waitcnt vmcnt(2)
	v_mul_f32_e32 v63, 0xbfb8aa3b, v47
	v_exp_f32_e32 v60, v60
	v_exp_f32_e32 v61, v61
	v_mul_f32_e32 v30, v30, v50
	v_mul_f32_e32 v31, v31, v51
	v_mul_f32_e32 v32, v32, v52
	v_mul_f32_e32 v33, v33, v53
	v_exp_f32_e32 v62, v62
	v_exp_f32_e32 v63, v63
	v_mul_f32_e32 v34, v34, v54
	v_mul_f32_e32 v35, v35, v55
	v_mul_f32_e32 v36, v36, v56
	v_mul_f32_e32 v37, v37, v57
	v_mul_f32_e32 v42, v42, v58
	v_mul_f32_e32 v43, v43, v59
	ds_write2st64_b32 v41, v30, v31 offset1:1
	ds_write2st64_b32 v41, v32, v33 offset0:2 offset1:3
	ds_write2st64_b32 v41, v34, v35 offset0:4 offset1:5
	ds_write2st64_b32 v41, v36, v37 offset0:6 offset1:7
	ds_write2st64_b32 v41, v42, v43 offset0:8 offset1:9
	s_waitcnt vmcnt(1)
	v_mul_f32_e32 v32, 0xbfb8aa3b, v48
	s_waitcnt vmcnt(0)
	v_mul_f32_e32 v33, 0xbfb8aa3b, v49
	v_exp_f32_e32 v32, v32
	v_exp_f32_e32 v33, v33
	v_add_f32_e32 v60, 1.0, v60
	v_add_f32_e32 v61, 1.0, v61
	v_add_f32_e32 v62, 1.0, v62
	v_rcp_f32_e32 v60, v60
	v_rcp_f32_e32 v61, v61
	v_add_f32_e32 v31, 1.0, v63
	v_rcp_f32_e32 v62, v62
	v_rcp_f32_e32 v31, v31
	v_add_f32_e32 v32, 1.0, v32
	v_add_f32_e32 v33, 1.0, v33
	v_rcp_f32_e32 v32, v32
	v_rcp_f32_e32 v33, v33
	v_mul_f32_e32 v44, v44, v60
	v_mul_f32_e32 v30, v45, v61
	ds_write2st64_b32 v41, v44, v30 offset0:10 offset1:11
	v_mul_f32_e32 v30, v46, v62
	v_mul_f32_e32 v31, v47, v31
	ds_write2st64_b32 v41, v30, v31 offset0:12 offset1:13
	v_mul_f32_e32 v30, v48, v32
	v_mul_f32_e32 v31, v49, v33
	ds_write2st64_b32 v41, v30, v31 offset0:14 offset1:15
	v_lshl_or_b32 v30, s39, 6, v0
	s_ashr_i32 s39, s38, 31
	s_lshl_b64 s[40:41], s[38:39], 11
	s_add_u32 s39, s40, s42
	s_addc_u32 s40, s41, s43
	s_mulk_i32 s40, 0x6000
	s_mul_hi_u32 s41, s39, 0x6000
	s_waitcnt lgkmcnt(0)
	s_add_i32 s41, s41, s40
	s_mulk_i32 s39, 0x6000
	s_add_u32 s40, s12, s39
	s_addc_u32 s41, s13, s41
	v_ashrrev_i32_e32 v31, 31, v30
	v_mov_b32_e32 v34, 0
	v_lshl_add_u64 v[32:33], v[30:31], 2, s[40:41]
	s_mov_b64 s[40:41], 0
	s_mov_b32 s39, s2
	v_mov_b32_e32 v35, v34
	v_mov_b32_e32 v36, v34
	v_mov_b32_e32 v37, v34
	v_lshl_add_u64 v[42:43], v[32:33], 0, s[40:41]
	s_movk_i32 s46, 0x6000
	v_add_co_u32_e32 v44, vcc, s46, v42
	s_mov_b32 s46, 0xc000
	s_nop 0
	v_addc_co_u32_e32 v45, vcc, 0, v43, vcc
	v_add_co_u32_e32 v46, vcc, s46, v42
	s_mov_b32 s46, 0x12000
	s_nop 0
	v_addc_co_u32_e32 v47, vcc, 0, v43, vcc
	v_add_co_u32_e32 v48, vcc, s46, v42
	s_mov_b32 s46, 0x18000
	s_nop 0
	v_addc_co_u32_e32 v49, vcc, 0, v43, vcc
	global_load_dword v74, v[42:43], off
	v_add_co_u32_e32 v50, vcc, s46, v42
	s_mov_b32 s46, 0x1e000
	s_nop 0
	v_addc_co_u32_e32 v51, vcc, 0, v43, vcc
	v_add_co_u32_e32 v52, vcc, s46, v42
	s_mov_b32 s46, 0x24000
	s_nop 0
	v_addc_co_u32_e32 v53, vcc, 0, v43, vcc
	v_add_co_u32_e32 v54, vcc, s46, v42
	s_mov_b32 s46, 0x2a000
	s_nop 0
	v_addc_co_u32_e32 v55, vcc, 0, v43, vcc
	v_add_co_u32_e32 v42, vcc, s46, v42
	v_mov_b32_e32 v31, s39
	s_nop 0
	v_addc_co_u32_e32 v43, vcc, 0, v43, vcc
	global_load_dword v76, v[44:45], off
	global_load_dword v78, v[46:47], off
	global_load_dword v80, v[48:49], off
	global_load_dword v82, v[50:51], off
	global_load_dword v84, v[52:53], off
	global_load_dword v86, v[54:55], off
	global_load_dword v88, v[42:43], off
; __device__ __forceinline__ void phase_convert(const Args& a, LAS unsigned char* lds) {
;     ...
;         for (int ii = 0; ii < 256; ++ii) { const float w = wp[(size_t)ii * (3 * D)]; a0 += scr[ii] * w; a1 += scr[256 + ii] * w; a2 += scr[512 + ii] * w; a3 += scr[768 + ii] * w; }
.LBB0_462:
	s_add_u32 s40, s40, 0x30000
	s_cmp_eq_u32 s40, 0x600000
	s_cselect_b32 s40, 0, s40
	v_lshl_add_u64 v[42:43], v[32:33], 0, s[40:41]
	s_movk_i32 s46, 0x6000
	v_add_co_u32_e32 v44, vcc, s46, v42
	s_mov_b32 s46, 0xc000
	s_nop 0
	v_addc_co_u32_e32 v45, vcc, 0, v43, vcc
	v_add_co_u32_e32 v46, vcc, s46, v42
	s_mov_b32 s46, 0x12000
	s_nop 0
	v_addc_co_u32_e32 v47, vcc, 0, v43, vcc
	v_add_co_u32_e32 v48, vcc, s46, v42
	s_mov_b32 s46, 0x18000
	s_nop 0
	v_addc_co_u32_e32 v49, vcc, 0, v43, vcc
	global_load_dword v94, v[42:43], off
	v_add_co_u32_e32 v50, vcc, s46, v42
	s_mov_b32 s46, 0x1e000
	s_nop 0
	v_addc_co_u32_e32 v51, vcc, 0, v43, vcc
	v_add_co_u32_e32 v52, vcc, s46, v42
	s_mov_b32 s46, 0x24000
	s_nop 0
	v_addc_co_u32_e32 v53, vcc, 0, v43, vcc
	v_add_co_u32_e32 v54, vcc, s46, v42
	s_mov_b32 s46, 0x2a000
	s_nop 0
	v_addc_co_u32_e32 v55, vcc, 0, v43, vcc
	v_add_co_u32_e32 v42, vcc, s46, v42
	v_mov_b32_e32 v31, s39
	s_nop 0
	v_addc_co_u32_e32 v43, vcc, 0, v43, vcc
	global_load_dword v96, v[44:45], off
	global_load_dword v98, v[46:47], off
	global_load_dword v100, v[48:49], off
	global_load_dword v102, v[50:51], off
	global_load_dword v104, v[52:53], off
	global_load_dword v106, v[54:55], off
	global_load_dword v108, v[42:43], off
	ds_read_b128 v[42:45], v31
	ds_read_b128 v[46:49], v31 offset:16
	ds_read_b128 v[50:53], v31 offset:1024
	ds_read_b128 v[54:57], v31 offset:1040
	ds_read_b128 v[58:61], v31 offset:2048
	ds_read_b128 v[62:65], v31 offset:2064
	ds_read_b128 v[66:69], v31 offset:3072
	ds_read_b128 v[70:73], v31 offset:3088
	s_waitcnt lgkmcnt(7)
	v_mov_b32_e32 v90, v42
	s_waitcnt lgkmcnt(5)
	v_mov_b32_e32 v91, v50
	s_waitcnt lgkmcnt(3)
	v_mov_b32_e32 v92, v58
	s_waitcnt lgkmcnt(1)
	v_mov_b32_e32 v93, v66
	v_mov_b32_e32 v50, v43
	v_mov_b32_e32 v66, v59
	v_mov_b32_e32 v42, v44
	v_mov_b32_e32 v43, v52
	v_mov_b32_e32 v58, v60
	v_mov_b32_e32 v59, v68
	v_mov_b32_e32 v52, v45
	v_mov_b32_e32 v68, v61
	v_mov_b32_e32 v44, v46
	v_mov_b32_e32 v45, v54
	v_mov_b32_e32 v60, v62
	s_waitcnt lgkmcnt(0)
	v_mov_b32_e32 v61, v70
	v_mov_b32_e32 v54, v47
	v_mov_b32_e32 v70, v63
	v_mov_b32_e32 v46, v48
	v_mov_b32_e32 v47, v56
	v_mov_b32_e32 v62, v64
	v_mov_b32_e32 v63, v72
	v_mov_b32_e32 v56, v49
	v_mov_b32_e32 v72, v65
	s_waitcnt vmcnt(15)
	v_pk_fma_f32 v[34:35], v[74:75], v[90:91], v[34:35] op_sel_hi:[0,1,1]
	v_pk_fma_f32 v[36:37], v[74:75], v[92:93], v[36:37] op_sel_hi:[0,1,1]
	s_waitcnt vmcnt(14)
	v_pk_fma_f32 v[34:35], v[76:77], v[50:51], v[34:35] op_sel_hi:[0,1,1]
	v_pk_fma_f32 v[36:37], v[76:77], v[66:67], v[36:37] op_sel_hi:[0,1,1]
	s_waitcnt vmcnt(13)
	v_pk_fma_f32 v[34:35], v[78:79], v[42:43], v[34:35] op_sel_hi:[0,1,1]
	v_pk_fma_f32 v[36:37], v[78:79], v[58:59], v[36:37] op_sel_hi:[0,1,1]
	s_waitcnt vmcnt(12)
	v_pk_fma_f32 v[34:35], v[80:81], v[52:53], v[34:35] op_sel_hi:[0,1,1]
	v_pk_fma_f32 v[36:37], v[80:81], v[68:69], v[36:37] op_sel_hi:[0,1,1]
	s_waitcnt vmcnt(11)
	v_pk_fma_f32 v[34:35], v[82:83], v[44:45], v[34:35] op_sel_hi:[0,1,1]
	v_pk_fma_f32 v[36:37], v[82:83], v[60:61], v[36:37] op_sel_hi:[0,1,1]
	s_waitcnt vmcnt(10)
	v_pk_fma_f32 v[34:35], v[84:85], v[54:55], v[34:35] op_sel_hi:[0,1,1]
	v_pk_fma_f32 v[36:37], v[84:85], v[70:71], v[36:37] op_sel_hi:[0,1,1]
	s_waitcnt vmcnt(9)
	v_pk_fma_f32 v[34:35], v[86:87], v[46:47], v[34:35] op_sel_hi:[0,1,1]
	v_pk_fma_f32 v[36:37], v[86:87], v[62:63], v[36:37] op_sel_hi:[0,1,1]
	s_waitcnt vmcnt(8)
; __device__ __forceinline__ void phase_convert(const Args& a, LAS unsigned char* lds) {
;     ...
;         for (int ii = 0; ii < 256; ++ii) { const float w = wp[(size_t)ii * (3 * D)]; a0 += scr[ii] * w; a1 += scr[256 + ii] * w; a2 += scr[512 + ii] * w; a3 += scr[768 + ii] * w; }
;         red[(wave * 4 + 0) * 64 + lane] = a0; red[(wave * 4 + 1) * 64 + lane] = a1; red[(wave * 4 + 2) * 64 + lane] = a2; red[(wave * 4 + 3) * 64 + lane] = a3;
;         __syncthreads();
;         if (wave < 4) { float t = a.in[I_ADAB][l * 3 * D + j];
; #pragma unroll
;             for (int w = 0; w < 8; ++w) t += red[(w * 4 + wave) * 64 + lane];
;             MOD[(l * 4 + wave) * 6144 + j] = t; }
	v_pk_fma_f32 v[34:35], v[88:89], v[56:57], v[34:35] op_sel_hi:[0,1,1]
	v_pk_fma_f32 v[36:37], v[88:89], v[72:73], v[36:37] op_sel_hi:[0,1,1]
	s_add_i32 s39, s39, 32
	s_add_u32 s40, s40, 0x30000
	s_cmp_eq_u32 s40, 0x600000
	s_cselect_b32 s40, 0, s40
	v_lshl_add_u64 v[42:43], v[32:33], 0, s[40:41]
	s_movk_i32 s46, 0x6000
	v_add_co_u32_e32 v44, vcc, s46, v42
	s_mov_b32 s46, 0xc000
	s_nop 0
	v_addc_co_u32_e32 v45, vcc, 0, v43, vcc
	v_add_co_u32_e32 v46, vcc, s46, v42
	s_mov_b32 s46, 0x12000
	s_nop 0
	v_addc_co_u32_e32 v47, vcc, 0, v43, vcc
	v_add_co_u32_e32 v48, vcc, s46, v42
	s_mov_b32 s46, 0x18000
	s_nop 0
	v_addc_co_u32_e32 v49, vcc, 0, v43, vcc
	global_load_dword v74, v[42:43], off
	v_add_co_u32_e32 v50, vcc, s46, v42
	s_mov_b32 s46, 0x1e000
	s_nop 0
	v_addc_co_u32_e32 v51, vcc, 0, v43, vcc
	v_add_co_u32_e32 v52, vcc, s46, v42
	s_mov_b32 s46, 0x24000
	s_nop 0
	v_addc_co_u32_e32 v53, vcc, 0, v43, vcc
	v_add_co_u32_e32 v54, vcc, s46, v42
	s_mov_b32 s46, 0x2a000
	s_nop 0
	v_addc_co_u32_e32 v55, vcc, 0, v43, vcc
	v_add_co_u32_e32 v42, vcc, s46, v42
	v_mov_b32_e32 v31, s39
	s_nop 0
	v_addc_co_u32_e32 v43, vcc, 0, v43, vcc
	global_load_dword v76, v[44:45], off
	global_load_dword v78, v[46:47], off
	global_load_dword v80, v[48:49], off
	global_load_dword v82, v[50:51], off
	global_load_dword v84, v[52:53], off
	global_load_dword v86, v[54:55], off
	global_load_dword v88, v[42:43], off
	ds_read_b128 v[42:45], v31
	ds_read_b128 v[46:49], v31 offset:16
	ds_read_b128 v[50:53], v31 offset:1024
	ds_read_b128 v[54:57], v31 offset:1040
	ds_read_b128 v[58:61], v31 offset:2048
	ds_read_b128 v[62:65], v31 offset:2064
	ds_read_b128 v[66:69], v31 offset:3072
	ds_read_b128 v[70:73], v31 offset:3088
	s_waitcnt lgkmcnt(7)
	v_mov_b32_e32 v90, v42
	s_waitcnt lgkmcnt(5)
	v_mov_b32_e32 v91, v50
	s_waitcnt lgkmcnt(3)
	v_mov_b32_e32 v92, v58
	s_waitcnt lgkmcnt(1)
	v_mov_b32_e32 v93, v66
	v_mov_b32_e32 v50, v43
	v_mov_b32_e32 v66, v59
	v_mov_b32_e32 v42, v44
	v_mov_b32_e32 v43, v52
	v_mov_b32_e32 v58, v60
	v_mov_b32_e32 v59, v68
	v_mov_b32_e32 v52, v45
	v_mov_b32_e32 v68, v61
	v_mov_b32_e32 v44, v46
	v_mov_b32_e32 v45, v54
	v_mov_b32_e32 v60, v62
	s_waitcnt lgkmcnt(0)
	v_mov_b32_e32 v61, v70
	v_mov_b32_e32 v54, v47
	v_mov_b32_e32 v70, v63
	v_mov_b32_e32 v46, v48
	v_mov_b32_e32 v47, v56
	v_mov_b32_e32 v62, v64
	v_mov_b32_e32 v63, v72
	v_mov_b32_e32 v56, v49
	v_mov_b32_e32 v72, v65
	s_waitcnt vmcnt(15)
	v_pk_fma_f32 v[34:35], v[94:95], v[90:91], v[34:35] op_sel_hi:[0,1,1]
	v_pk_fma_f32 v[36:37], v[94:95], v[92:93], v[36:37] op_sel_hi:[0,1,1]
	s_waitcnt vmcnt(14)
	v_pk_fma_f32 v[34:35], v[96:97], v[50:51], v[34:35] op_sel_hi:[0,1,1]
	v_pk_fma_f32 v[36:37], v[96:97], v[66:67], v[36:37] op_sel_hi:[0,1,1]
	s_waitcnt vmcnt(13)
	v_pk_fma_f32 v[34:35], v[98:99], v[42:43], v[34:35] op_sel_hi:[0,1,1]
	v_pk_fma_f32 v[36:37], v[98:99], v[58:59], v[36:37] op_sel_hi:[0,1,1]
	s_waitcnt vmcnt(12)
	v_pk_fma_f32 v[34:35], v[100:101], v[52:53], v[34:35] op_sel_hi:[0,1,1]
	v_pk_fma_f32 v[36:37], v[100:101], v[68:69], v[36:37] op_sel_hi:[0,1,1]
	s_waitcnt vmcnt(11)
	v_pk_fma_f32 v[34:35], v[102:103], v[44:45], v[34:35] op_sel_hi:[0,1,1]
	v_pk_fma_f32 v[36:37], v[102:103], v[60:61], v[36:37] op_sel_hi:[0,1,1]
	s_waitcnt vmcnt(10)
	v_pk_fma_f32 v[34:35], v[104:105], v[54:55], v[34:35] op_sel_hi:[0,1,1]
	v_pk_fma_f32 v[36:37], v[104:105], v[70:71], v[36:37] op_sel_hi:[0,1,1]
	s_waitcnt vmcnt(9)
	v_pk_fma_f32 v[34:35], v[106:107], v[46:47], v[34:35] op_sel_hi:[0,1,1]
	v_pk_fma_f32 v[36:37], v[106:107], v[62:63], v[36:37] op_sel_hi:[0,1,1]
	s_waitcnt vmcnt(8)
	v_pk_fma_f32 v[34:35], v[108:109], v[56:57], v[34:35] op_sel_hi:[0,1,1]
	v_pk_fma_f32 v[36:37], v[108:109], v[72:73], v[36:37] op_sel_hi:[0,1,1]
	s_add_i32 s39, s39, 32
	s_sub_i32 s46, s39, s2
	s_cmpk_lg_i32 s46, 0x400
	s_cbranch_scc1 .LBB0_462
	v_add_u32_e32 v31, s44, v39
	s_and_b64 vcc, exec, s[0:1]
	ds_write2st64_b32 v31, v34, v35 offset1:1
	ds_write2st64_b32 v31, v36, v37 offset0:2 offset1:3
	s_waitcnt lgkmcnt(0)
	s_barrier
	s_cbranch_vccz .LBB0_460
	s_mul_i32 s39, s38, 0x1800
	v_add_u32_e32 v32, s39, v30
	v_ashrrev_i32_e32 v33, 31, v32
	v_lshl_add_u64 v[32:33], v[32:33], 2, s[14:15]
	global_load_dword v44, v[32:33], off
	ds_read2st64_b32 v[32:33], v40 offset1:4
	ds_read2st64_b32 v[34:35], v40 offset0:8 offset1:12
	ds_read2st64_b32 v[36:37], v40 offset0:16 offset1:20
	ds_read2st64_b32 v[42:43], v40 offset0:24 offset1:28
	s_lshl_b32 s38, s38, 2
	s_add_i32 s38, s38, s3
	s_mulk_i32 s38, 0x1800
	v_add_u32_e32 v30, s38, v30
	v_ashrrev_i32_e32 v31, 31, v30
	v_lshl_add_u64 v[30:31], v[30:31], 2, s[28:29]
	s_waitcnt vmcnt(0) lgkmcnt(3)
	v_add_f32_e32 v32, v44, v32
	v_add_f32_e32 v32, v32, v33
	s_waitcnt lgkmcnt(2)
	v_add_f32_e32 v32, v32, v34
	v_add_f32_e32 v32, v32, v35
	s_waitcnt lgkmcnt(1)
	v_add_f32_e32 v32, v32, v36
	v_add_f32_e32 v32, v32, v37
	s_waitcnt lgkmcnt(0)
	v_add_f32_e32 v32, v32, v42
	v_add_f32_e32 v32, v32, v43
	global_store_dword v[30:31], v32, off
	s_branch .LBB0_460
